# QKV epilogue (k/v tiles): the four norm-gain vector loads issue back to back behind one wait instead of four serial waits
# baseline (speedup 1.0000x reference)
; #define PG8_STAGE(bufoff, gbase, voff) do { _Pragma("unroll") for (int _i = 0; _i < 2; ++_i) \
;         __builtin_amdgcn_global_load_lds((const unsigned*)((const char*)(gbase) + (voff)[_i]), (LAS unsigned*)(lds + (bufoff) + ldsw + _i * 8192), 16, 0, 0); } while (0)
; #define PG8_LDA(dst, b, h) do { _Pragma("unroll") for (int m = 0; m < 4; ++m) _Pragma("unroll") for (int k = 0; k < 2; ++k) dst[m][k] = *(const LAS bf16x8*)(lds + PG8_SA(b, h) + aoff + m * 2048 + k * 1024); } while (0)
; #define PG8_LDB(dst, b, h) do { _Pragma("unroll") for (int n = 0; n < 2; ++n) _Pragma("unroll") for (int k = 0; k < 2; ++k) dst[n][k] = *(const LAS bf16x8*)(lds + PG8_SB(b, h) + boff + n * 2048 + k * 1024); } while (0)
; #define PG8_MMA(ai, bj, At, Bt) do { __builtin_amdgcn_s_setprio(1); _Pragma("unroll") for (int m = 0; m < 4; ++m) _Pragma("unroll") for (int n = 0; n < 2; ++n) _Pragma("unroll") for (int k = 0; k < 2; ++k) \
;         acc[ai][bj][m][n] = __builtin_amdgcn_mfma_f32_16x16x32_bf16(Bt[n][k], At[m][k], acc[ai][bj][m][n], 0, 0, 0); __builtin_amdgcn_s_setprio(0); } while (0)
; #define PG8_WAIT_V(n) asm volatile("s_waitcnt vmcnt(" #n ")" ::: "memory")
; #define PG8_WAIT_L(n) asm volatile("s_waitcnt lgkmcnt(" #n ")" ::: "memory")
; #define PG8_BAR __builtin_amdgcn_s_barrier()
; #define PG8_SCHED __builtin_amdgcn_sched_barrier(0)
; template <class Epi>
; __device__ __forceinline__ void gemm_phase(LAS unsigned char* lds, const Gemm g, const StaticOrder& S, const Epi& E) {
;     ...
;             PG8_LDB(B0, 0, 0); PG8_SCHED; PG8_LDA(At, 0, 0); PG8_STAGE(PG8_SA(1, 1), a1 + hstepA, voffA);
;             PG8_WAIT_L(8); PG8_BAR; PG8_WAIT_L(0); PG8_MMA(0, 0, At, B0); PG8_BAR; PG8_SCHED;
;             PG8_LDB(B1, 0, 1); PG8_STAGE(PG8_SB(0, 0), b2, voffB);
;             PG8_BAR; PG8_WAIT_L(0); PG8_MMA(0, 1, At, B1); PG8_BAR;
;             PG8_LDA(At, 0, 1); PG8_STAGE(PG8_SA(0, 0), a2, voffA);
;             PG8_BAR; PG8_WAIT_L(0); PG8_MMA(1, 0, At, B0); PG8_BAR; PG8_SCHED;
;             PG8_STAGE(PG8_SB(0, 1), b2 + hstepB, voffB);
;             PG8_WAIT_V(6); PG8_BAR; PG8_MMA(1, 1, At, B1); PG8_BAR;
.LBB0_1583:
	ds_read_b128 v[80:83], v180
	ds_read_b128 v[84:87], v180 offset:1024
	ds_read_b128 v[88:91], v180 offset:2048
	ds_read_b128 v[92:95], v180 offset:3072
	s_add_u32 s14, s12, 0xfffc0080
	s_addc_u32 s15, s13, -1
	s_cmp_eq_u32 s74, 12
	s_cselect_b32 s37, s25, s15
	s_cselect_b32 s36, s31, s14
	s_cselect_b32 s15, s23, s39
	s_cselect_b32 s14, s35, s38
	v_lshl_add_u64 v[210:211], s[12:13], 0, v[158:159]
	s_add_i32 m0, s8, 0xc000
	ds_read_b128 v[166:169], v181
	ds_read_b128 v[170:173], v181 offset:1024
	ds_read_b128 v[186:189], v181 offset:2048
	ds_read_b128 v[190:193], v181 offset:3072
	ds_read_b128 v[194:197], v181 offset:4096
	ds_read_b128 v[198:201], v181 offset:5120
	ds_read_b128 v[202:205], v181 offset:6144
	ds_read_b128 v[206:209], v181 offset:7168
	global_load_lds_dwordx4 v[210:211], off
	v_lshl_add_u64 v[210:211], s[12:13], 0, v[160:161]
	s_add_i32 m0, s8, 0xe000
	s_nop 0
	global_load_lds_dwordx4 v[210:211], off
	ds_read_b128 v[210:213], v182
	ds_read_b128 v[214:217], v182 offset:1024
	ds_read_b128 v[220:223], v182 offset:2048
	ds_read_b128 v[224:227], v182 offset:3072
	s_waitcnt lgkmcnt(0)
	s_barrier
	s_setprio 1
	v_mfma_f32_16x16x32_bf16 v[140:143], v[80:83], v[166:169], v[140:143]
	v_mfma_f32_16x16x32_bf16 v[136:139], v[88:91], v[166:169], v[136:139]
	v_mfma_f32_16x16x32_bf16 v[124:127], v[80:83], v[186:189], v[124:127]
	v_mfma_f32_16x16x32_bf16 v[120:123], v[88:91], v[186:189], v[120:123]
	v_mfma_f32_16x16x32_bf16 v[108:111], v[80:83], v[194:197], v[108:111]
	v_mfma_f32_16x16x32_bf16 v[104:107], v[88:91], v[194:197], v[104:107]
	v_mfma_f32_16x16x32_bf16 v[76:79], v[80:83], v[202:205], v[76:79]
	v_mfma_f32_16x16x32_bf16 v[72:75], v[88:91], v[202:205], v[72:75]
	v_mfma_f32_16x16x32_bf16 v[140:143], v[84:87], v[170:173], v[140:143]
	v_mfma_f32_16x16x32_bf16 v[136:139], v[92:95], v[170:173], v[136:139]
	v_mfma_f32_16x16x32_bf16 v[124:127], v[84:87], v[190:193], v[124:127]
	v_mfma_f32_16x16x32_bf16 v[120:123], v[92:95], v[190:193], v[120:123]
	v_mfma_f32_16x16x32_bf16 v[108:111], v[84:87], v[198:201], v[108:111]
	v_mfma_f32_16x16x32_bf16 v[104:107], v[92:95], v[198:201], v[104:107]
	v_mfma_f32_16x16x32_bf16 v[76:79], v[84:87], v[206:209], v[76:79]
	v_mfma_f32_16x16x32_bf16 v[72:75], v[92:95], v[206:209], v[72:75]
	v_mfma_f32_16x16x32_bf16 v[132:135], v[210:213], v[166:169], v[132:135]
	v_mfma_f32_16x16x32_bf16 v[128:131], v[220:223], v[166:169], v[128:131]
	v_mfma_f32_16x16x32_bf16 v[116:119], v[210:213], v[186:189], v[116:119]
	v_mfma_f32_16x16x32_bf16 v[112:115], v[220:223], v[186:189], v[112:115]
	v_mfma_f32_16x16x32_bf16 v[100:103], v[210:213], v[194:197], v[100:103]
	v_mfma_f32_16x16x32_bf16 v[96:99], v[220:223], v[194:197], v[96:99]
	v_mfma_f32_16x16x32_bf16 v[68:71], v[210:213], v[202:205], v[68:71]
	v_mfma_f32_16x16x32_bf16 v[64:67], v[220:223], v[202:205], v[64:67]
	v_mfma_f32_16x16x32_bf16 v[132:135], v[214:217], v[170:173], v[132:135]
	v_mfma_f32_16x16x32_bf16 v[128:131], v[224:227], v[170:173], v[128:131]
	v_mfma_f32_16x16x32_bf16 v[116:119], v[214:217], v[190:193], v[116:119]
	v_mfma_f32_16x16x32_bf16 v[112:115], v[224:227], v[190:193], v[112:115]
	v_mfma_f32_16x16x32_bf16 v[100:103], v[214:217], v[198:201], v[100:103]
	v_mfma_f32_16x16x32_bf16 v[96:99], v[224:227], v[198:201], v[96:99]
	v_mfma_f32_16x16x32_bf16 v[68:71], v[214:217], v[206:209], v[68:71]
	v_mfma_f32_16x16x32_bf16 v[64:67], v[224:227], v[206:209], v[64:67]
	s_setprio 0
	s_barrier
	s_nop 1
	ds_read_b128 v[166:169], v181 offset:16384
	ds_read_b128 v[170:173], v181 offset:17408
	ds_read_b128 v[186:189], v181 offset:18432
	ds_read_b128 v[190:193], v181 offset:19456
	ds_read_b128 v[194:197], v181 offset:20480
	ds_read_b128 v[198:201], v181 offset:21504
	ds_read_b128 v[202:205], v181 offset:22528
	ds_read_b128 v[206:209], v181 offset:23552
	s_add_i32 s75, s48, s7
	v_lshl_add_u64 v[228:229], s[14:15], 0, v[146:147]
	s_mov_b32 m0, s75
	s_nop 0
	global_load_lds_dwordx4 v[228:229], off
	v_lshl_add_u64 v[230:231], s[14:15], 0, v[150:151]
	s_add_i32 m0, s75, 0x2000
	s_nop 0
	global_load_lds_dwordx4 v[230:231], off
	s_mov_b32 m0, s8
	v_lshl_add_u64 v[232:233], s[36:37], 0, v[144:145]
	global_load_lds_dwordx4 v[232:233], off
	v_lshl_add_u64 v[236:237], s[36:37], 0, v[148:149]
	s_mov_b32 m0, s9
	s_nop 0
	global_load_lds_dwordx4 v[236:237], off
	s_add_u32 s76, s14, 0x40000
	s_addc_u32 s77, s15, 0
	s_add_i32 s75, s49, s7
	v_lshl_add_u64 v[254:255], s[76:77], 0, v[146:147]
	s_mov_b32 m0, s75
	s_nop 0
	global_load_lds_dwordx4 v[254:255], off
	v_lshl_add_u64 v[254:255], s[76:77], 0, v[150:151]
	s_add_i32 m0, s75, 0x2000
	s_nop 0
	global_load_lds_dwordx4 v[254:255], off
	s_waitcnt vmcnt(6)
	s_waitcnt lgkmcnt(0)
	s_barrier
; #define PG8_STAGE(bufoff, gbase, voff) do { _Pragma("unroll") for (int _i = 0; _i < 2; ++_i) \
;         __builtin_amdgcn_global_load_lds((const unsigned*)((const char*)(gbase) + (voff)[_i]), (LAS unsigned*)(lds + (bufoff) + ldsw + _i * 8192), 16, 0, 0); } while (0)
; #define PG8_LDA(dst, b, h) do { _Pragma("unroll") for (int m = 0; m < 4; ++m) _Pragma("unroll") for (int k = 0; k < 2; ++k) dst[m][k] = *(const LAS bf16x8*)(lds + PG8_SA(b, h) + aoff + m * 2048 + k * 1024); } while (0)
; #define PG8_LDB(dst, b, h) do { _Pragma("unroll") for (int n = 0; n < 2; ++n) _Pragma("unroll") for (int k = 0; k < 2; ++k) dst[n][k] = *(const LAS bf16x8*)(lds + PG8_SB(b, h) + boff + n * 2048 + k * 1024); } while (0)
; #define PG8_MMA(ai, bj, At, Bt) do { __builtin_amdgcn_s_setprio(1); _Pragma("unroll") for (int m = 0; m < 4; ++m) _Pragma("unroll") for (int n = 0; n < 2; ++n) _Pragma("unroll") for (int k = 0; k < 2; ++k) \
;         acc[ai][bj][m][n] = __builtin_amdgcn_mfma_f32_16x16x32_bf16(Bt[n][k], At[m][k], acc[ai][bj][m][n], 0, 0, 0); __builtin_amdgcn_s_setprio(0); } while (0)
; #define PG8_WAIT_V(n) asm volatile("s_waitcnt vmcnt(" #n ")" ::: "memory")
; #define PG8_WAIT_L(n) asm volatile("s_waitcnt lgkmcnt(" #n ")" ::: "memory")
; #define PG8_BAR __builtin_amdgcn_s_barrier()
; #define PG8_SCHED __builtin_amdgcn_sched_barrier(0)
; template <class Epi>
; __device__ __forceinline__ void gemm_phase(LAS unsigned char* lds, const Gemm g, const StaticOrder& S, const Epi& E) {
;     ...
;             PG8_WAIT_V(6); PG8_BAR; PG8_MMA(1, 1, At, B1); PG8_BAR;
;             PG8_LDB(B0, 1, 0); PG8_SCHED; PG8_LDA(At, 1, 0); PG8_STAGE(PG8_SA(0, 1), a2 + hstepA, voffA);
;             PG8_WAIT_L(8); PG8_BAR; PG8_WAIT_L(0); PG8_MMA(0, 0, At, B0); PG8_BAR; PG8_SCHED;
;             PG8_LDB(B1, 1, 1); PG8_STAGE(PG8_SB(1, 0), b3, voffB);
;             PG8_BAR; PG8_WAIT_L(0); PG8_MMA(0, 1, At, B1); PG8_BAR;
;             PG8_LDA(At, 1, 1); PG8_STAGE(PG8_SA(1, 0), a3, voffA);
;             PG8_BAR; PG8_WAIT_L(0); PG8_MMA(1, 0, At, B0); PG8_BAR; PG8_SCHED;
	s_setprio 1
	v_mfma_f32_16x16x32_bf16 v[60:63], v[80:83], v[166:169], v[60:63]
	v_mfma_f32_16x16x32_bf16 v[56:59], v[88:91], v[166:169], v[56:59]
	v_mfma_f32_16x16x32_bf16 v[44:47], v[80:83], v[186:189], v[44:47]
	v_mfma_f32_16x16x32_bf16 v[40:43], v[88:91], v[186:189], v[40:43]
	v_mfma_f32_16x16x32_bf16 v[28:31], v[80:83], v[194:197], v[28:31]
	v_mfma_f32_16x16x32_bf16 v[24:27], v[88:91], v[194:197], v[24:27]
	v_mfma_f32_16x16x32_bf16 v[12:15], v[80:83], v[202:205], v[12:15]
	v_mfma_f32_16x16x32_bf16 v[8:11], v[88:91], v[202:205], v[8:11]
	v_mfma_f32_16x16x32_bf16 v[60:63], v[84:87], v[170:173], v[60:63]
	v_mfma_f32_16x16x32_bf16 v[56:59], v[92:95], v[170:173], v[56:59]
	v_mfma_f32_16x16x32_bf16 v[44:47], v[84:87], v[190:193], v[44:47]
	v_mfma_f32_16x16x32_bf16 v[40:43], v[92:95], v[190:193], v[40:43]
	v_mfma_f32_16x16x32_bf16 v[28:31], v[84:87], v[198:201], v[28:31]
	v_mfma_f32_16x16x32_bf16 v[24:27], v[92:95], v[198:201], v[24:27]
	v_mfma_f32_16x16x32_bf16 v[12:15], v[84:87], v[206:209], v[12:15]
	v_mfma_f32_16x16x32_bf16 v[8:11], v[92:95], v[206:209], v[8:11]
	v_mfma_f32_16x16x32_bf16 v[52:55], v[210:213], v[166:169], v[52:55]
	v_mfma_f32_16x16x32_bf16 v[48:51], v[220:223], v[166:169], v[48:51]
	v_mfma_f32_16x16x32_bf16 v[36:39], v[210:213], v[186:189], v[36:39]
	v_mfma_f32_16x16x32_bf16 v[32:35], v[220:223], v[186:189], v[32:35]
	v_mfma_f32_16x16x32_bf16 v[20:23], v[210:213], v[194:197], v[20:23]
	v_mfma_f32_16x16x32_bf16 v[16:19], v[220:223], v[194:197], v[16:19]
	v_mfma_f32_16x16x32_bf16 v[4:7], v[210:213], v[202:205], v[4:7]
	v_mfma_f32_16x16x32_bf16 v[0:3], v[220:223], v[202:205], v[0:3]
	v_mfma_f32_16x16x32_bf16 v[52:55], v[214:217], v[170:173], v[52:55]
	v_mfma_f32_16x16x32_bf16 v[48:51], v[224:227], v[170:173], v[48:51]
	v_mfma_f32_16x16x32_bf16 v[36:39], v[214:217], v[190:193], v[36:39]
	v_mfma_f32_16x16x32_bf16 v[32:35], v[224:227], v[190:193], v[32:35]
	v_mfma_f32_16x16x32_bf16 v[20:23], v[214:217], v[198:201], v[20:23]
	v_mfma_f32_16x16x32_bf16 v[16:19], v[224:227], v[198:201], v[16:19]
	v_mfma_f32_16x16x32_bf16 v[4:7], v[214:217], v[206:209], v[4:7]
	v_mfma_f32_16x16x32_bf16 v[0:3], v[224:227], v[206:209], v[0:3]
	s_setprio 0
	s_add_i32 s75, 0, 0x18000
	v_add_u32_e32 v92, s75, v175
	s_barrier
	ds_read_b128 v[80:83], v92
	ds_read_b128 v[84:87], v92 offset:1024
	ds_read_b128 v[88:91], v92 offset:2048
	ds_read_b128 v[92:95], v92 offset:3072
	s_add_u32 s36, s36, 0x40000
	s_addc_u32 s37, s37, 0
	s_mov_b32 m0, s40
	v_lshl_add_u64 v[210:211], s[36:37], 0, v[144:145]
	ds_read_b128 v[166:169], v181 offset:32768
	ds_read_b128 v[170:173], v181 offset:33792
	ds_read_b128 v[186:189], v181 offset:34816
	ds_read_b128 v[190:193], v181 offset:35840
	ds_read_b128 v[194:197], v181 offset:36864
	ds_read_b128 v[198:201], v181 offset:37888
	ds_read_b128 v[202:205], v181 offset:38912
	ds_read_b128 v[206:209], v181 offset:39936
	global_load_lds_dwordx4 v[210:211], off
	v_lshl_add_u64 v[210:211], s[36:37], 0, v[148:149]
	s_mov_b32 m0, s41
	s_nop 0
	global_load_lds_dwordx4 v[210:211], off
	s_add_i32 s36, 0, 0x1c000
	v_add_u32_e32 v152, s36, v175
	ds_read_b128 v[210:213], v152
	ds_read_b128 v[214:217], v152 offset:1024
	ds_read_b128 v[220:223], v152 offset:2048
	ds_read_b128 v[224:227], v152 offset:3072
	s_waitcnt lgkmcnt(0)
	s_barrier
	s_setprio 1
	v_mfma_f32_16x16x32_bf16 v[140:143], v[80:83], v[166:169], v[140:143]
	v_mfma_f32_16x16x32_bf16 v[136:139], v[88:91], v[166:169], v[136:139]
	v_mfma_f32_16x16x32_bf16 v[124:127], v[80:83], v[186:189], v[124:127]
	v_mfma_f32_16x16x32_bf16 v[120:123], v[88:91], v[186:189], v[120:123]
	v_mfma_f32_16x16x32_bf16 v[108:111], v[80:83], v[194:197], v[108:111]
	v_mfma_f32_16x16x32_bf16 v[104:107], v[88:91], v[194:197], v[104:107]
	v_mfma_f32_16x16x32_bf16 v[76:79], v[80:83], v[202:205], v[76:79]
	v_mfma_f32_16x16x32_bf16 v[72:75], v[88:91], v[202:205], v[72:75]
	v_mfma_f32_16x16x32_bf16 v[140:143], v[84:87], v[170:173], v[140:143]
	v_mfma_f32_16x16x32_bf16 v[136:139], v[92:95], v[170:173], v[136:139]
	v_mfma_f32_16x16x32_bf16 v[124:127], v[84:87], v[190:193], v[124:127]
	v_mfma_f32_16x16x32_bf16 v[120:123], v[92:95], v[190:193], v[120:123]
	v_mfma_f32_16x16x32_bf16 v[108:111], v[84:87], v[198:201], v[108:111]
	v_mfma_f32_16x16x32_bf16 v[104:107], v[92:95], v[198:201], v[104:107]
	v_mfma_f32_16x16x32_bf16 v[76:79], v[84:87], v[206:209], v[76:79]
	v_mfma_f32_16x16x32_bf16 v[72:75], v[92:95], v[206:209], v[72:75]
	v_mfma_f32_16x16x32_bf16 v[132:135], v[210:213], v[166:169], v[132:135]
	v_mfma_f32_16x16x32_bf16 v[128:131], v[220:223], v[166:169], v[128:131]
	v_mfma_f32_16x16x32_bf16 v[116:119], v[210:213], v[186:189], v[116:119]
	v_mfma_f32_16x16x32_bf16 v[112:115], v[220:223], v[186:189], v[112:115]
	v_mfma_f32_16x16x32_bf16 v[100:103], v[210:213], v[194:197], v[100:103]
	v_mfma_f32_16x16x32_bf16 v[96:99], v[220:223], v[194:197], v[96:99]
	v_mfma_f32_16x16x32_bf16 v[68:71], v[210:213], v[202:205], v[68:71]
	v_mfma_f32_16x16x32_bf16 v[64:67], v[220:223], v[202:205], v[64:67]
	v_mfma_f32_16x16x32_bf16 v[132:135], v[214:217], v[170:173], v[132:135]
	v_mfma_f32_16x16x32_bf16 v[128:131], v[224:227], v[170:173], v[128:131]
	v_mfma_f32_16x16x32_bf16 v[116:119], v[214:217], v[190:193], v[116:119]
	v_mfma_f32_16x16x32_bf16 v[112:115], v[224:227], v[190:193], v[112:115]
	v_mfma_f32_16x16x32_bf16 v[100:103], v[214:217], v[198:201], v[100:103]
	v_mfma_f32_16x16x32_bf16 v[96:99], v[224:227], v[198:201], v[96:99]
	v_mfma_f32_16x16x32_bf16 v[68:71], v[214:217], v[206:209], v[68:71]
	v_mfma_f32_16x16x32_bf16 v[64:67], v[224:227], v[206:209], v[64:67]
	s_setprio 0
	s_barrier
; #define PG8_STAGE(bufoff, gbase, voff) do { _Pragma("unroll") for (int _i = 0; _i < 2; ++_i) \
;         __builtin_amdgcn_global_load_lds((const unsigned*)((const char*)(gbase) + (voff)[_i]), (LAS unsigned*)(lds + (bufoff) + ldsw + _i * 8192), 16, 0, 0); } while (0)
; #define PG8_MMA(ai, bj, At, Bt) do { __builtin_amdgcn_s_setprio(1); _Pragma("unroll") for (int m = 0; m < 4; ++m) _Pragma("unroll") for (int n = 0; n < 2; ++n) _Pragma("unroll") for (int k = 0; k < 2; ++k) \
;         acc[ai][bj][m][n] = __builtin_amdgcn_mfma_f32_16x16x32_bf16(Bt[n][k], At[m][k], acc[ai][bj][m][n], 0, 0, 0); __builtin_amdgcn_s_setprio(0); } while (0)
; #define PG8_WAIT_V(n) asm volatile("s_waitcnt vmcnt(" #n ")" ::: "memory")
; #define PG8_WAIT_L(n) asm volatile("s_waitcnt lgkmcnt(" #n ")" ::: "memory")
; #define PG8_BAR __builtin_amdgcn_s_barrier()
; #define PG8_SCHED __builtin_amdgcn_sched_barrier(0)
; template <class Epi>
; __device__ __forceinline__ void gemm_phase(LAS unsigned char* lds, const Gemm g, const StaticOrder& S, const Epi& E) {
;     ...
;             PG8_BAR; PG8_WAIT_L(0); PG8_MMA(1, 0, At, B0); PG8_BAR; PG8_SCHED;
;             PG8_STAGE(PG8_SB(1, 1), b3 + hstepB, voffB);
;             PG8_WAIT_V(6); PG8_BAR; PG8_MMA(1, 1, At, B1); PG8_BAR;
;     __device__ __forceinline__ void operator()(AccRef acc, const Unit& u, int wr, int wc, int fr, int fq) const {
;     ...
;         for (int bj = 0; bj < 2; ++bj)
; #pragma unroll
;             for (int n = 0; n < 2; ++n) { const f32x4 a = *(const f32x4*)(qg + 32 * bj + 8 * fq + 4 * n), b = *(const f32x4*)(kg + 32 * bj + 8 * fq + 4 * n);
;                 gv[bj][n] = which == 0 ? a : (which == 1 ? b : (f32x4){1.f, 1.f, 1.f, 1.f}); }
	s_nop 1
	ds_read_b128 v[166:169], v181 offset:49152
	ds_read_b128 v[170:173], v181 offset:50176
	ds_read_b128 v[186:189], v181 offset:51200
	ds_read_b128 v[190:193], v181 offset:52224
	ds_read_b128 v[194:197], v181 offset:53248
	ds_read_b128 v[198:201], v181 offset:54272
	ds_read_b128 v[202:205], v181 offset:55296
	ds_read_b128 v[206:209], v181 offset:56320
	s_add_i32 s37, s75, s7
	v_lshl_add_u64 v[254:255], v[228:229], 0, s[16:17]
	s_mov_b32 m0, s37
	s_nop 0
	global_load_lds_dwordx4 v[254:255], off
	v_lshl_add_u64 v[254:255], v[230:231], 0, s[16:17]
	s_add_i32 m0, s37, 0x2000
	s_nop 0
	global_load_lds_dwordx4 v[254:255], off
	s_mov_b32 m0, s45
	v_lshl_add_u64 v[254:255], v[232:233], 0, s[16:17]
	global_load_lds_dwordx4 v[254:255], off
	v_lshl_add_u64 v[228:229], v[236:237], 0, s[16:17]
	s_mov_b32 m0, s46
	s_nop 0
	global_load_lds_dwordx4 v[228:229], off
	s_add_u32 s14, s14, 0x40080
	s_addc_u32 s15, s15, 0
	s_add_i32 s36, s36, s7
	v_lshl_add_u64 v[254:255], s[14:15], 0, v[146:147]
	s_mov_b32 m0, s36
	s_nop 0
	global_load_lds_dwordx4 v[254:255], off
	v_lshl_add_u64 v[254:255], s[14:15], 0, v[150:151]
	s_add_i32 m0, s36, 0x2000
	s_nop 0
	global_load_lds_dwordx4 v[254:255], off
	s_waitcnt vmcnt(6)
	s_waitcnt lgkmcnt(0)
	s_barrier
	s_setprio 1
	v_mfma_f32_16x16x32_bf16 v[60:63], v[80:83], v[166:169], v[60:63]
	v_mfma_f32_16x16x32_bf16 v[56:59], v[88:91], v[166:169], v[56:59]
	v_mfma_f32_16x16x32_bf16 v[44:47], v[80:83], v[186:189], v[44:47]
	v_mfma_f32_16x16x32_bf16 v[40:43], v[88:91], v[186:189], v[40:43]
	v_mfma_f32_16x16x32_bf16 v[28:31], v[80:83], v[194:197], v[28:31]
	v_mfma_f32_16x16x32_bf16 v[24:27], v[88:91], v[194:197], v[24:27]
	v_mfma_f32_16x16x32_bf16 v[12:15], v[80:83], v[202:205], v[12:15]
	v_mfma_f32_16x16x32_bf16 v[8:11], v[88:91], v[202:205], v[8:11]
	v_mfma_f32_16x16x32_bf16 v[60:63], v[84:87], v[170:173], v[60:63]
	v_mfma_f32_16x16x32_bf16 v[56:59], v[92:95], v[170:173], v[56:59]
	v_mfma_f32_16x16x32_bf16 v[44:47], v[84:87], v[190:193], v[44:47]
	v_mfma_f32_16x16x32_bf16 v[40:43], v[92:95], v[190:193], v[40:43]
	v_mfma_f32_16x16x32_bf16 v[28:31], v[84:87], v[198:201], v[28:31]
	v_mfma_f32_16x16x32_bf16 v[24:27], v[92:95], v[198:201], v[24:27]
	v_mfma_f32_16x16x32_bf16 v[12:15], v[84:87], v[206:209], v[12:15]
	v_mfma_f32_16x16x32_bf16 v[8:11], v[92:95], v[206:209], v[8:11]
	v_mfma_f32_16x16x32_bf16 v[52:55], v[210:213], v[166:169], v[52:55]
	v_mfma_f32_16x16x32_bf16 v[48:51], v[220:223], v[166:169], v[48:51]
	v_mfma_f32_16x16x32_bf16 v[36:39], v[210:213], v[186:189], v[36:39]
	v_mfma_f32_16x16x32_bf16 v[32:35], v[220:223], v[186:189], v[32:35]
	v_mfma_f32_16x16x32_bf16 v[20:23], v[210:213], v[194:197], v[20:23]
	v_mfma_f32_16x16x32_bf16 v[16:19], v[220:223], v[194:197], v[16:19]
	v_mfma_f32_16x16x32_bf16 v[4:7], v[210:213], v[202:205], v[4:7]
	v_mfma_f32_16x16x32_bf16 v[0:3], v[220:223], v[202:205], v[0:3]
	v_mfma_f32_16x16x32_bf16 v[52:55], v[214:217], v[170:173], v[52:55]
	v_mfma_f32_16x16x32_bf16 v[48:51], v[224:227], v[170:173], v[48:51]
	v_mfma_f32_16x16x32_bf16 v[36:39], v[214:217], v[190:193], v[36:39]
	v_mfma_f32_16x16x32_bf16 v[32:35], v[224:227], v[190:193], v[32:35]
	v_mfma_f32_16x16x32_bf16 v[20:23], v[214:217], v[198:201], v[20:23]
	v_mfma_f32_16x16x32_bf16 v[16:19], v[224:227], v[198:201], v[16:19]
	v_mfma_f32_16x16x32_bf16 v[4:7], v[214:217], v[206:209], v[4:7]
	v_mfma_f32_16x16x32_bf16 v[0:3], v[224:227], v[206:209], v[0:3]
	s_setprio 0
	s_add_i32 s74, s74, 2
	s_add_u32 s12, s12, 0x100
	s_addc_u32 s13, s13, 0
	s_add_u32 s38, s38, 0x100
	s_addc_u32 s39, s39, 0
	s_cmp_gt_u32 s74, 13
	s_barrier
	s_cbranch_scc0 .LBB0_1583
	s_ashr_i32 s36, s30, 2
	s_cmp_gt_u32 s30, 3
	s_cselect_b64 s[38:39], -1, 0
	s_cmp_eq_u32 s36, 1
	s_mov_b64 s[14:15], -1
	s_cselect_b64 s[12:13], -1, 0
	s_and_b64 vcc, exec, s[38:39]
	s_cbranch_vccz .LBB0_1586
	global_load_dwordx4 v[80:83], v[154:155], off
	s_mov_b64 s[14:15], 0
.LBB0_1586:
	s_andn2_b64 vcc, exec, s[14:15]
	s_cbranch_vccnz .LBB0_1588
	global_load_dwordx4 v[80:83], v[156:157], off
.LBB0_1588:
	v_cndmask_b32_e64 v84, 0, 1, s[38:39]
	v_cmp_ne_u32_e64 s[14:15], 1, v84
	s_andn2_b64 vcc, exec, s[38:39]
	s_mov_b64 s[38:39], -1
	s_cbranch_vccnz .LBB0_1594
	global_load_dwordx4 v[88:91], v[154:155], off offset:16
	s_cbranch_execz .LBB0_1595

;     __device__ __forceinline__ void operator()(AccRef acc, const Unit& u, int wr, int wc, int fr, int fq) const {
;     ...
;             for (int n = 0; n < 2; ++n) { const f32x4 a = *(const f32x4*)(qg + 32 * bj + 8 * fq + 4 * n), b = *(const f32x4*)(kg + 32 * bj + 8 * fq + 4 * n);
;                 gv[bj][n] = which == 0 ? a : (which == 1 ? b : (f32x4){1.f, 1.f, 1.f, 1.f}); }
.LBB0_1591:
	global_load_dwordx4 v[84:87], v[154:155], off offset:128
	s_cbranch_execz .LBB0_1597

;     __device__ __forceinline__ void operator()(AccRef acc, const Unit& u, int wr, int wc, int fr, int fq) const {
;     ...
;             for (int n = 0; n < 2; ++n) { const f32x4 a = *(const f32x4*)(qg + 32 * bj + 8 * fq + 4 * n), b = *(const f32x4*)(kg + 32 * bj + 8 * fq + 4 * n);
;                 gv[bj][n] = which == 0 ? a : (which == 1 ? b : (f32x4){1.f, 1.f, 1.f, 1.f}); }
.LBB0_1593:
	global_load_dwordx4 v[92:95], v[154:155], off offset:144
	s_waitcnt vmcnt(0)
	v_cndmask_b32_e64 v83, 1.0, v83, s[12:13]
	v_cndmask_b32_e64 v82, 1.0, v82, s[12:13]
	v_cndmask_b32_e64 v81, 1.0, v81, s[12:13]
	v_cndmask_b32_e64 v80, 1.0, v80, s[12:13]
	v_cndmask_b32_e64 v91, 1.0, v91, s[12:13]
	v_cndmask_b32_e64 v90, 1.0, v90, s[12:13]
	v_cndmask_b32_e64 v89, 1.0, v89, s[12:13]
	v_cndmask_b32_e64 v88, 1.0, v88, s[12:13]
	v_cndmask_b32_e64 v87, 1.0, v87, s[12:13]
	v_cndmask_b32_e64 v86, 1.0, v86, s[12:13]
	v_cndmask_b32_e64 v85, 1.0, v85, s[12:13]
	v_cndmask_b32_e64 v84, 1.0, v84, s[12:13]
	v_cndmask_b32_e64 v95, 1.0, v95, s[12:13]
	v_cndmask_b32_e64 v94, 1.0, v94, s[12:13]
	v_cndmask_b32_e64 v93, 1.0, v93, s[12:13]
	v_cndmask_b32_e64 v92, 1.0, v92, s[12:13]
	s_mov_b32 s23, 1.0
	s_cbranch_execz .LBB0_1599
	s_branch .LBB0_1600
